# hand-written final RMSNorm: all four rows of a wave loaded up front, gain loaded once
# speedup vs baseline: 1.0073x; 1.0073x over previous
.LBB0_1856:
	v_readlane_b32 s1, v253, 0
	s_lshl_b32 s1, s1, 3
	v_readfirstlane_b32 s0, v214
	s_ashr_i32 s0, s0, 6
	s_add_i32 s2, s1, s0
	v_readlane_b32 s10, v254, 38
	s_cmpk_gt_i32 s2, 0x1fff
	v_readlane_b32 s11, v254, 39
	s_cbranch_scc1 .LBB0_1859
	v_and_b32_e32 v176, 63, v214
	v_lshlrev_b32_e32 v176, 4, v176
	v_readlane_b32 s4, v253, 1
	v_readlane_b32 s5, v253, 2
	v_readlane_b32 s12, v253, 5
	s_lshl_b32 s12, s12, 3
	s_add_u32 s4, s4, 0x1000
	s_addc_u32 s5, s5, 0
	global_load_dwordx4 v[128:131], v176, s[4:5] offset:-4096
	global_load_dwordx4 v[132:135], v176, s[4:5] offset:-3072
	global_load_dwordx4 v[136:139], v176, s[4:5] offset:-2048
	global_load_dwordx4 v[140:143], v176, s[4:5] offset:-1024
	global_load_dwordx4 v[144:147], v176, s[4:5] offset:0
	global_load_dwordx4 v[148:151], v176, s[4:5] offset:1024
	global_load_dwordx4 v[152:155], v176, s[4:5] offset:2048
	global_load_dwordx4 v[156:159], v176, s[4:5] offset:3072
	s_mov_b32 s3, 0
	s_mov_b32 s13, s2
	s_cmpk_lt_i32 s13, 0x2000
	s_cbranch_scc0 .Lfin_issued
	s_lshr_b32 s6, s13, 11
	s_mul_i32 s6, s6, 0x900
	s_and_b32 s7, s13, 0x7ff
	s_add_i32 s6, s6, s7
	s_addk_i32 s6, 0x100
	s_lshl_b32 s6, s6, 13
	v_readlane_b32 s8, v253, 50
	v_readlane_b32 s9, v253, 51
	s_add_u32 s6, s6, 0x1000
	s_add_u32 s8, s8, s6
	s_addc_u32 s9, s9, 0
	global_load_dwordx4 v[0:3], v176, s[8:9] offset:-4096
	global_load_dwordx4 v[4:7], v176, s[8:9] offset:-3072
	global_load_dwordx4 v[8:11], v176, s[8:9] offset:-2048
	global_load_dwordx4 v[12:15], v176, s[8:9] offset:-1024
	global_load_dwordx4 v[16:19], v176, s[8:9] offset:0
	global_load_dwordx4 v[20:23], v176, s[8:9] offset:1024
	global_load_dwordx4 v[24:27], v176, s[8:9] offset:2048
	global_load_dwordx4 v[28:31], v176, s[8:9] offset:3072
	s_add_i32 s3, s3, 1
	s_add_i32 s13, s13, s12
	s_cmpk_lt_i32 s13, 0x2000
	s_cbranch_scc0 .Lfin_issued
	s_lshr_b32 s6, s13, 11
	s_mul_i32 s6, s6, 0x900
	s_and_b32 s7, s13, 0x7ff
	s_add_i32 s6, s6, s7
	s_addk_i32 s6, 0x100
	s_lshl_b32 s6, s6, 13
	v_readlane_b32 s8, v253, 50
	v_readlane_b32 s9, v253, 51
	s_add_u32 s6, s6, 0x1000
	s_add_u32 s8, s8, s6
	s_addc_u32 s9, s9, 0
	global_load_dwordx4 v[32:35], v176, s[8:9] offset:-4096
	global_load_dwordx4 v[36:39], v176, s[8:9] offset:-3072
	global_load_dwordx4 v[40:43], v176, s[8:9] offset:-2048
	global_load_dwordx4 v[44:47], v176, s[8:9] offset:-1024
	global_load_dwordx4 v[48:51], v176, s[8:9] offset:0
	global_load_dwordx4 v[52:55], v176, s[8:9] offset:1024
	global_load_dwordx4 v[56:59], v176, s[8:9] offset:2048
	global_load_dwordx4 v[60:63], v176, s[8:9] offset:3072
	s_add_i32 s3, s3, 1
	s_add_i32 s13, s13, s12
	s_cmpk_lt_i32 s13, 0x2000
	s_cbranch_scc0 .Lfin_issued
	s_lshr_b32 s6, s13, 11
	s_mul_i32 s6, s6, 0x900
	s_and_b32 s7, s13, 0x7ff
	s_add_i32 s6, s6, s7
	s_addk_i32 s6, 0x100
	s_lshl_b32 s6, s6, 13
	v_readlane_b32 s8, v253, 50
	v_readlane_b32 s9, v253, 51
	s_add_u32 s6, s6, 0x1000
	s_add_u32 s8, s8, s6
	s_addc_u32 s9, s9, 0
	global_load_dwordx4 v[64:67], v176, s[8:9] offset:-4096
	global_load_dwordx4 v[68:71], v176, s[8:9] offset:-3072
	global_load_dwordx4 v[72:75], v176, s[8:9] offset:-2048
	global_load_dwordx4 v[76:79], v176, s[8:9] offset:-1024
	global_load_dwordx4 v[80:83], v176, s[8:9] offset:0
	global_load_dwordx4 v[84:87], v176, s[8:9] offset:1024
	global_load_dwordx4 v[88:91], v176, s[8:9] offset:2048
	global_load_dwordx4 v[92:95], v176, s[8:9] offset:3072
	s_add_i32 s3, s3, 1
	s_add_i32 s13, s13, s12
	s_cmpk_lt_i32 s13, 0x2000
	s_cbranch_scc0 .Lfin_issued
	s_lshr_b32 s6, s13, 11
	s_mul_i32 s6, s6, 0x900
	s_and_b32 s7, s13, 0x7ff
	s_add_i32 s6, s6, s7
	s_addk_i32 s6, 0x100
	s_lshl_b32 s6, s6, 13
	v_readlane_b32 s8, v253, 50
	v_readlane_b32 s9, v253, 51
	s_add_u32 s6, s6, 0x1000
	s_add_u32 s8, s8, s6
	s_addc_u32 s9, s9, 0
	global_load_dwordx4 v[96:99], v176, s[8:9] offset:-4096
	global_load_dwordx4 v[100:103], v176, s[8:9] offset:-3072
	global_load_dwordx4 v[104:107], v176, s[8:9] offset:-2048
	global_load_dwordx4 v[108:111], v176, s[8:9] offset:-1024
	global_load_dwordx4 v[112:115], v176, s[8:9] offset:0
	global_load_dwordx4 v[116:119], v176, s[8:9] offset:1024
	global_load_dwordx4 v[120:123], v176, s[8:9] offset:2048
	global_load_dwordx4 v[124:127], v176, s[8:9] offset:3072
	s_add_i32 s3, s3, 1
	s_add_i32 s13, s13, s12
.Lfin_issued:
	s_cmp_eq_u32 s3, 4
	s_cbranch_scc1 .Lfin_fast
	s_waitcnt vmcnt(0)
.Lfin_fast:
	s_cmp_le_u32 s3, 0
	s_cbranch_scc1 .Lfin_done
	s_waitcnt vmcnt(24)
	v_mul_f32_e32 v160, v0, v0
	v_mul_f32_e32 v161, v1, v1
	v_mul_f32_e32 v162, v2, v2
	v_mul_f32_e32 v163, v3, v3
	v_fmac_f32_e32 v160, v4, v4
	v_fmac_f32_e32 v161, v5, v5
	v_fmac_f32_e32 v162, v6, v6
	v_fmac_f32_e32 v163, v7, v7
	v_fmac_f32_e32 v160, v8, v8
	v_fmac_f32_e32 v161, v9, v9
	v_fmac_f32_e32 v162, v10, v10
	v_fmac_f32_e32 v163, v11, v11
	v_fmac_f32_e32 v160, v12, v12
	v_fmac_f32_e32 v161, v13, v13
	v_fmac_f32_e32 v162, v14, v14
	v_fmac_f32_e32 v163, v15, v15
	v_fmac_f32_e32 v160, v16, v16
	v_fmac_f32_e32 v161, v17, v17
	v_fmac_f32_e32 v162, v18, v18
	v_fmac_f32_e32 v163, v19, v19
	v_fmac_f32_e32 v160, v20, v20
	v_fmac_f32_e32 v161, v21, v21
	v_fmac_f32_e32 v162, v22, v22
	v_fmac_f32_e32 v163, v23, v23
	v_fmac_f32_e32 v160, v24, v24
	v_fmac_f32_e32 v161, v25, v25
	v_fmac_f32_e32 v162, v26, v26
	v_fmac_f32_e32 v163, v27, v27
	v_fmac_f32_e32 v160, v28, v28
	v_fmac_f32_e32 v161, v29, v29
	v_fmac_f32_e32 v162, v30, v30
	v_fmac_f32_e32 v163, v31, v31
	v_add_f32_e32 v160, v160, v161
	v_add_f32_e32 v162, v162, v163
	v_add_f32_e32 v160, v160, v162
	s_nop 1
	v_add_f32_dpp v160, v160, v160 quad_perm:[1,0,3,2] row_mask:0xf bank_mask:0xf
	s_nop 1
	v_add_f32_dpp v160, v160, v160 quad_perm:[2,3,0,1] row_mask:0xf bank_mask:0xf
	s_nop 1
	v_add_f32_dpp v160, v160, v160 row_half_mirror row_mask:0xf bank_mask:0xf
	s_nop 1
	v_add_f32_dpp v160, v160, v160 row_mirror row_mask:0xf bank_mask:0xf
	s_nop 1
	v_mov_b32_e32 v161, v160
	s_nop 1
	v_permlane16_swap_b32_e32 v160, v161
	s_nop 1
	v_add_f32_e32 v160, v160, v161
	v_mov_b32_e32 v161, v160
	s_nop 1
	v_permlane32_swap_b32_e32 v160, v161
	s_nop 1
	v_add_f32_e32 v164, v160, v161
	v_mov_b32_e32 v170, 0x358637bd
	v_fmamk_f32 v164, v164, 0x3a000000, v170
	v_mul_f32_e32 v165, 0x4f800000, v164
	v_cmp_gt_f32_e32 vcc, 0xf800000, v164
	s_nop 1
	v_cndmask_b32_e32 v164, v164, v165, vcc
	v_sqrt_f32_e32 v165, v164
	s_nop 0
	v_add_u32_e32 v166, -1, v165
	v_fma_f32 v167, -v166, v165, v164
	v_cmp_ge_f32_e64 s[14:15], 0, v167
	v_add_u32_e32 v167, 1, v165
	s_nop 0
	v_cndmask_b32_e64 v166, v165, v166, s[14:15]
	v_fma_f32 v165, -v167, v165, v164
	v_cmp_lt_f32_e64 s[14:15], 0, v165
	s_nop 1
	v_cndmask_b32_e64 v165, v166, v167, s[14:15]
	v_mul_f32_e32 v166, 0x37800000, v165
	v_cndmask_b32_e32 v165, v165, v166, vcc
	v_mov_b32_e32 v171, 0x260
	v_cmp_class_f32_e32 vcc, v164, v171
	s_nop 1
	v_cndmask_b32_e32 v164, v165, v164, vcc
	v_div_scale_f32 v165, s[14:15], v164, v164, 1.0
	v_rcp_f32_e32 v166, v165
	s_nop 1
	v_fma_f32 v167, -v165, v166, 1.0
	v_fmac_f32_e32 v166, v167, v166
	v_div_scale_f32 v167, vcc, 1.0, v164, 1.0
	v_mul_f32_e32 v168, v167, v166
	v_fma_f32 v169, -v165, v168, v167
	v_fmac_f32_e32 v168, v169, v166
	v_fma_f32 v165, -v165, v168, v167
	s_nop 0
	v_div_fmas_f32 v165, v165, v166, v168
	v_div_fixup_f32 v164, v165, v164, 1.0
	s_mul_i32 s6, s12, 0
	s_add_i32 s6, s6, s2
	s_lshl_b32 s6, s6, 13
	v_readlane_b32 s8, v253, 3
	v_readlane_b32 s9, v253, 4
	s_add_u32 s6, s6, 0x1000
	s_add_u32 s8, s8, s6
	s_addc_u32 s9, s9, 0
	v_pk_mul_f32 v[0:1], v[0:1], v[164:165] op_sel_hi:[1,0]
	v_pk_mul_f32 v[0:1], v[0:1], v[128:129]
	v_pk_mul_f32 v[2:3], v[2:3], v[164:165] op_sel_hi:[1,0]
	v_pk_mul_f32 v[2:3], v[2:3], v[130:131]
	global_store_dwordx4 v176, v[0:3], s[8:9] offset:-4096
	v_pk_mul_f32 v[4:5], v[4:5], v[164:165] op_sel_hi:[1,0]
	v_pk_mul_f32 v[4:5], v[4:5], v[132:133]
	v_pk_mul_f32 v[6:7], v[6:7], v[164:165] op_sel_hi:[1,0]
	v_pk_mul_f32 v[6:7], v[6:7], v[134:135]
	global_store_dwordx4 v176, v[4:7], s[8:9] offset:-3072
	v_pk_mul_f32 v[8:9], v[8:9], v[164:165] op_sel_hi:[1,0]
	v_pk_mul_f32 v[8:9], v[8:9], v[136:137]
	v_pk_mul_f32 v[10:11], v[10:11], v[164:165] op_sel_hi:[1,0]
	v_pk_mul_f32 v[10:11], v[10:11], v[138:139]
	global_store_dwordx4 v176, v[8:11], s[8:9] offset:-2048
	v_pk_mul_f32 v[12:13], v[12:13], v[164:165] op_sel_hi:[1,0]
	v_pk_mul_f32 v[12:13], v[12:13], v[140:141]
	v_pk_mul_f32 v[14:15], v[14:15], v[164:165] op_sel_hi:[1,0]
	v_pk_mul_f32 v[14:15], v[14:15], v[142:143]
	global_store_dwordx4 v176, v[12:15], s[8:9] offset:-1024
	v_pk_mul_f32 v[16:17], v[16:17], v[164:165] op_sel_hi:[1,0]
	v_pk_mul_f32 v[16:17], v[16:17], v[144:145]
	v_pk_mul_f32 v[18:19], v[18:19], v[164:165] op_sel_hi:[1,0]
	v_pk_mul_f32 v[18:19], v[18:19], v[146:147]
	global_store_dwordx4 v176, v[16:19], s[8:9] offset:0
	v_pk_mul_f32 v[20:21], v[20:21], v[164:165] op_sel_hi:[1,0]
	v_pk_mul_f32 v[20:21], v[20:21], v[148:149]
	v_pk_mul_f32 v[22:23], v[22:23], v[164:165] op_sel_hi:[1,0]
	v_pk_mul_f32 v[22:23], v[22:23], v[150:151]
	global_store_dwordx4 v176, v[20:23], s[8:9] offset:1024
	v_pk_mul_f32 v[24:25], v[24:25], v[164:165] op_sel_hi:[1,0]
	v_pk_mul_f32 v[24:25], v[24:25], v[152:153]
	v_pk_mul_f32 v[26:27], v[26:27], v[164:165] op_sel_hi:[1,0]
	v_pk_mul_f32 v[26:27], v[26:27], v[154:155]
	global_store_dwordx4 v176, v[24:27], s[8:9] offset:2048
	v_pk_mul_f32 v[28:29], v[28:29], v[164:165] op_sel_hi:[1,0]
	v_pk_mul_f32 v[28:29], v[28:29], v[156:157]
	v_pk_mul_f32 v[30:31], v[30:31], v[164:165] op_sel_hi:[1,0]
	v_pk_mul_f32 v[30:31], v[30:31], v[158:159]
	global_store_dwordx4 v176, v[28:31], s[8:9] offset:3072
	s_cmp_le_u32 s3, 1
	s_cbranch_scc1 .Lfin_done
	s_waitcnt vmcnt(24)
	v_mul_f32_e32 v160, v32, v32
	v_mul_f32_e32 v161, v33, v33
	v_mul_f32_e32 v162, v34, v34
	v_mul_f32_e32 v163, v35, v35
	v_fmac_f32_e32 v160, v36, v36
	v_fmac_f32_e32 v161, v37, v37
	v_fmac_f32_e32 v162, v38, v38
	v_fmac_f32_e32 v163, v39, v39
	v_fmac_f32_e32 v160, v40, v40
	v_fmac_f32_e32 v161, v41, v41
	v_fmac_f32_e32 v162, v42, v42
	v_fmac_f32_e32 v163, v43, v43
	v_fmac_f32_e32 v160, v44, v44
	v_fmac_f32_e32 v161, v45, v45
	v_fmac_f32_e32 v162, v46, v46
	v_fmac_f32_e32 v163, v47, v47
	v_fmac_f32_e32 v160, v48, v48
	v_fmac_f32_e32 v161, v49, v49
	v_fmac_f32_e32 v162, v50, v50
	v_fmac_f32_e32 v163, v51, v51
	v_fmac_f32_e32 v160, v52, v52
	v_fmac_f32_e32 v161, v53, v53
	v_fmac_f32_e32 v162, v54, v54
	v_fmac_f32_e32 v163, v55, v55
	v_fmac_f32_e32 v160, v56, v56
	v_fmac_f32_e32 v161, v57, v57
	v_fmac_f32_e32 v162, v58, v58
	v_fmac_f32_e32 v163, v59, v59
	v_fmac_f32_e32 v160, v60, v60
	v_fmac_f32_e32 v161, v61, v61
	v_fmac_f32_e32 v162, v62, v62
	v_fmac_f32_e32 v163, v63, v63
	v_add_f32_e32 v160, v160, v161
	v_add_f32_e32 v162, v162, v163
	v_add_f32_e32 v160, v160, v162
	s_nop 1
	v_add_f32_dpp v160, v160, v160 quad_perm:[1,0,3,2] row_mask:0xf bank_mask:0xf
	s_nop 1
	v_add_f32_dpp v160, v160, v160 quad_perm:[2,3,0,1] row_mask:0xf bank_mask:0xf
	s_nop 1
	v_add_f32_dpp v160, v160, v160 row_half_mirror row_mask:0xf bank_mask:0xf
	s_nop 1
	v_add_f32_dpp v160, v160, v160 row_mirror row_mask:0xf bank_mask:0xf
	s_nop 1
	v_mov_b32_e32 v161, v160
	s_nop 1
	v_permlane16_swap_b32_e32 v160, v161
	s_nop 1
	v_add_f32_e32 v160, v160, v161
	v_mov_b32_e32 v161, v160
	s_nop 1
	v_permlane32_swap_b32_e32 v160, v161
	s_nop 1
	v_add_f32_e32 v164, v160, v161
	v_mov_b32_e32 v170, 0x358637bd
	v_fmamk_f32 v164, v164, 0x3a000000, v170
	v_mul_f32_e32 v165, 0x4f800000, v164
	v_cmp_gt_f32_e32 vcc, 0xf800000, v164
	s_nop 1
	v_cndmask_b32_e32 v164, v164, v165, vcc
	v_sqrt_f32_e32 v165, v164
	s_nop 0
	v_add_u32_e32 v166, -1, v165
	v_fma_f32 v167, -v166, v165, v164
	v_cmp_ge_f32_e64 s[14:15], 0, v167
	v_add_u32_e32 v167, 1, v165
	s_nop 0
	v_cndmask_b32_e64 v166, v165, v166, s[14:15]
	v_fma_f32 v165, -v167, v165, v164
	v_cmp_lt_f32_e64 s[14:15], 0, v165
	s_nop 1
	v_cndmask_b32_e64 v165, v166, v167, s[14:15]
	v_mul_f32_e32 v166, 0x37800000, v165
	v_cndmask_b32_e32 v165, v165, v166, vcc
	v_mov_b32_e32 v171, 0x260
	v_cmp_class_f32_e32 vcc, v164, v171
	s_nop 1
	v_cndmask_b32_e32 v164, v165, v164, vcc
	v_div_scale_f32 v165, s[14:15], v164, v164, 1.0
	v_rcp_f32_e32 v166, v165
	s_nop 1
	v_fma_f32 v167, -v165, v166, 1.0
	v_fmac_f32_e32 v166, v167, v166
	v_div_scale_f32 v167, vcc, 1.0, v164, 1.0
	v_mul_f32_e32 v168, v167, v166
	v_fma_f32 v169, -v165, v168, v167
	v_fmac_f32_e32 v168, v169, v166
	v_fma_f32 v165, -v165, v168, v167
	s_nop 0
	v_div_fmas_f32 v165, v165, v166, v168
	v_div_fixup_f32 v164, v165, v164, 1.0
	s_mul_i32 s6, s12, 1
	s_add_i32 s6, s6, s2
	s_lshl_b32 s6, s6, 13
	v_readlane_b32 s8, v253, 3
	v_readlane_b32 s9, v253, 4
	s_add_u32 s6, s6, 0x1000
	s_add_u32 s8, s8, s6
	s_addc_u32 s9, s9, 0
	v_pk_mul_f32 v[32:33], v[32:33], v[164:165] op_sel_hi:[1,0]
	v_pk_mul_f32 v[32:33], v[32:33], v[128:129]
	v_pk_mul_f32 v[34:35], v[34:35], v[164:165] op_sel_hi:[1,0]
	v_pk_mul_f32 v[34:35], v[34:35], v[130:131]
	global_store_dwordx4 v176, v[32:35], s[8:9] offset:-4096
	v_pk_mul_f32 v[36:37], v[36:37], v[164:165] op_sel_hi:[1,0]
	v_pk_mul_f32 v[36:37], v[36:37], v[132:133]
	v_pk_mul_f32 v[38:39], v[38:39], v[164:165] op_sel_hi:[1,0]
	v_pk_mul_f32 v[38:39], v[38:39], v[134:135]
	global_store_dwordx4 v176, v[36:39], s[8:9] offset:-3072
	v_pk_mul_f32 v[40:41], v[40:41], v[164:165] op_sel_hi:[1,0]
	v_pk_mul_f32 v[40:41], v[40:41], v[136:137]
	v_pk_mul_f32 v[42:43], v[42:43], v[164:165] op_sel_hi:[1,0]
	v_pk_mul_f32 v[42:43], v[42:43], v[138:139]
	global_store_dwordx4 v176, v[40:43], s[8:9] offset:-2048
	v_pk_mul_f32 v[44:45], v[44:45], v[164:165] op_sel_hi:[1,0]
	v_pk_mul_f32 v[44:45], v[44:45], v[140:141]
	v_pk_mul_f32 v[46:47], v[46:47], v[164:165] op_sel_hi:[1,0]
	v_pk_mul_f32 v[46:47], v[46:47], v[142:143]
	global_store_dwordx4 v176, v[44:47], s[8:9] offset:-1024
	v_pk_mul_f32 v[48:49], v[48:49], v[164:165] op_sel_hi:[1,0]
	v_pk_mul_f32 v[48:49], v[48:49], v[144:145]
	v_pk_mul_f32 v[50:51], v[50:51], v[164:165] op_sel_hi:[1,0]
	v_pk_mul_f32 v[50:51], v[50:51], v[146:147]
	global_store_dwordx4 v176, v[48:51], s[8:9] offset:0
	v_pk_mul_f32 v[52:53], v[52:53], v[164:165] op_sel_hi:[1,0]
	v_pk_mul_f32 v[52:53], v[52:53], v[148:149]
	v_pk_mul_f32 v[54:55], v[54:55], v[164:165] op_sel_hi:[1,0]
	v_pk_mul_f32 v[54:55], v[54:55], v[150:151]
	global_store_dwordx4 v176, v[52:55], s[8:9] offset:1024
	v_pk_mul_f32 v[56:57], v[56:57], v[164:165] op_sel_hi:[1,0]
	v_pk_mul_f32 v[56:57], v[56:57], v[152:153]
	v_pk_mul_f32 v[58:59], v[58:59], v[164:165] op_sel_hi:[1,0]
	v_pk_mul_f32 v[58:59], v[58:59], v[154:155]
	global_store_dwordx4 v176, v[56:59], s[8:9] offset:2048
	v_pk_mul_f32 v[60:61], v[60:61], v[164:165] op_sel_hi:[1,0]
	v_pk_mul_f32 v[60:61], v[60:61], v[156:157]
	v_pk_mul_f32 v[62:63], v[62:63], v[164:165] op_sel_hi:[1,0]
	v_pk_mul_f32 v[62:63], v[62:63], v[158:159]
	global_store_dwordx4 v176, v[60:63], s[8:9] offset:3072
	s_cmp_le_u32 s3, 2
	s_cbranch_scc1 .Lfin_done
	s_waitcnt vmcnt(24)
	v_mul_f32_e32 v160, v64, v64
	v_mul_f32_e32 v161, v65, v65
	v_mul_f32_e32 v162, v66, v66
	v_mul_f32_e32 v163, v67, v67
	v_fmac_f32_e32 v160, v68, v68
	v_fmac_f32_e32 v161, v69, v69
	v_fmac_f32_e32 v162, v70, v70
	v_fmac_f32_e32 v163, v71, v71
	v_fmac_f32_e32 v160, v72, v72
	v_fmac_f32_e32 v161, v73, v73
	v_fmac_f32_e32 v162, v74, v74
	v_fmac_f32_e32 v163, v75, v75
	v_fmac_f32_e32 v160, v76, v76
	v_fmac_f32_e32 v161, v77, v77
	v_fmac_f32_e32 v162, v78, v78
	v_fmac_f32_e32 v163, v79, v79
	v_fmac_f32_e32 v160, v80, v80
	v_fmac_f32_e32 v161, v81, v81
	v_fmac_f32_e32 v162, v82, v82
	v_fmac_f32_e32 v163, v83, v83
	v_fmac_f32_e32 v160, v84, v84
	v_fmac_f32_e32 v161, v85, v85
	v_fmac_f32_e32 v162, v86, v86
	v_fmac_f32_e32 v163, v87, v87
	v_fmac_f32_e32 v160, v88, v88
	v_fmac_f32_e32 v161, v89, v89
	v_fmac_f32_e32 v162, v90, v90
	v_fmac_f32_e32 v163, v91, v91
	v_fmac_f32_e32 v160, v92, v92
	v_fmac_f32_e32 v161, v93, v93
	v_fmac_f32_e32 v162, v94, v94
	v_fmac_f32_e32 v163, v95, v95
	v_add_f32_e32 v160, v160, v161
	v_add_f32_e32 v162, v162, v163
	v_add_f32_e32 v160, v160, v162
	s_nop 1
	v_add_f32_dpp v160, v160, v160 quad_perm:[1,0,3,2] row_mask:0xf bank_mask:0xf
	s_nop 1
	v_add_f32_dpp v160, v160, v160 quad_perm:[2,3,0,1] row_mask:0xf bank_mask:0xf
	s_nop 1
	v_add_f32_dpp v160, v160, v160 row_half_mirror row_mask:0xf bank_mask:0xf
	s_nop 1
	v_add_f32_dpp v160, v160, v160 row_mirror row_mask:0xf bank_mask:0xf
	s_nop 1
	v_mov_b32_e32 v161, v160
	s_nop 1
	v_permlane16_swap_b32_e32 v160, v161
	s_nop 1
	v_add_f32_e32 v160, v160, v161
	v_mov_b32_e32 v161, v160
	s_nop 1
	v_permlane32_swap_b32_e32 v160, v161
	s_nop 1
	v_add_f32_e32 v164, v160, v161
	v_mov_b32_e32 v170, 0x358637bd
	v_fmamk_f32 v164, v164, 0x3a000000, v170
	v_mul_f32_e32 v165, 0x4f800000, v164
	v_cmp_gt_f32_e32 vcc, 0xf800000, v164
	s_nop 1
	v_cndmask_b32_e32 v164, v164, v165, vcc
	v_sqrt_f32_e32 v165, v164
	s_nop 0
	v_add_u32_e32 v166, -1, v165
	v_fma_f32 v167, -v166, v165, v164
	v_cmp_ge_f32_e64 s[14:15], 0, v167
	v_add_u32_e32 v167, 1, v165
	s_nop 0
	v_cndmask_b32_e64 v166, v165, v166, s[14:15]
	v_fma_f32 v165, -v167, v165, v164
	v_cmp_lt_f32_e64 s[14:15], 0, v165
	s_nop 1
	v_cndmask_b32_e64 v165, v166, v167, s[14:15]
	v_mul_f32_e32 v166, 0x37800000, v165
	v_cndmask_b32_e32 v165, v165, v166, vcc
	v_mov_b32_e32 v171, 0x260
	v_cmp_class_f32_e32 vcc, v164, v171
	s_nop 1
	v_cndmask_b32_e32 v164, v165, v164, vcc
	v_div_scale_f32 v165, s[14:15], v164, v164, 1.0
	v_rcp_f32_e32 v166, v165
	s_nop 1
	v_fma_f32 v167, -v165, v166, 1.0
	v_fmac_f32_e32 v166, v167, v166
	v_div_scale_f32 v167, vcc, 1.0, v164, 1.0
	v_mul_f32_e32 v168, v167, v166
	v_fma_f32 v169, -v165, v168, v167
	v_fmac_f32_e32 v168, v169, v166
	v_fma_f32 v165, -v165, v168, v167
	s_nop 0
	v_div_fmas_f32 v165, v165, v166, v168
	v_div_fixup_f32 v164, v165, v164, 1.0
	s_mul_i32 s6, s12, 2
	s_add_i32 s6, s6, s2
	s_lshl_b32 s6, s6, 13
	v_readlane_b32 s8, v253, 3
	v_readlane_b32 s9, v253, 4
	s_add_u32 s6, s6, 0x1000
	s_add_u32 s8, s8, s6
	s_addc_u32 s9, s9, 0
	v_pk_mul_f32 v[64:65], v[64:65], v[164:165] op_sel_hi:[1,0]
	v_pk_mul_f32 v[64:65], v[64:65], v[128:129]
	v_pk_mul_f32 v[66:67], v[66:67], v[164:165] op_sel_hi:[1,0]
	v_pk_mul_f32 v[66:67], v[66:67], v[130:131]
	global_store_dwordx4 v176, v[64:67], s[8:9] offset:-4096
	v_pk_mul_f32 v[68:69], v[68:69], v[164:165] op_sel_hi:[1,0]
	v_pk_mul_f32 v[68:69], v[68:69], v[132:133]
	v_pk_mul_f32 v[70:71], v[70:71], v[164:165] op_sel_hi:[1,0]
	v_pk_mul_f32 v[70:71], v[70:71], v[134:135]
	global_store_dwordx4 v176, v[68:71], s[8:9] offset:-3072
	v_pk_mul_f32 v[72:73], v[72:73], v[164:165] op_sel_hi:[1,0]
	v_pk_mul_f32 v[72:73], v[72:73], v[136:137]
	v_pk_mul_f32 v[74:75], v[74:75], v[164:165] op_sel_hi:[1,0]
	v_pk_mul_f32 v[74:75], v[74:75], v[138:139]
	global_store_dwordx4 v176, v[72:75], s[8:9] offset:-2048
	v_pk_mul_f32 v[76:77], v[76:77], v[164:165] op_sel_hi:[1,0]
	v_pk_mul_f32 v[76:77], v[76:77], v[140:141]
	v_pk_mul_f32 v[78:79], v[78:79], v[164:165] op_sel_hi:[1,0]
	v_pk_mul_f32 v[78:79], v[78:79], v[142:143]
	global_store_dwordx4 v176, v[76:79], s[8:9] offset:-1024
	v_pk_mul_f32 v[80:81], v[80:81], v[164:165] op_sel_hi:[1,0]
	v_pk_mul_f32 v[80:81], v[80:81], v[144:145]
	v_pk_mul_f32 v[82:83], v[82:83], v[164:165] op_sel_hi:[1,0]
	v_pk_mul_f32 v[82:83], v[82:83], v[146:147]
	global_store_dwordx4 v176, v[80:83], s[8:9] offset:0
	v_pk_mul_f32 v[84:85], v[84:85], v[164:165] op_sel_hi:[1,0]
	v_pk_mul_f32 v[84:85], v[84:85], v[148:149]
	v_pk_mul_f32 v[86:87], v[86:87], v[164:165] op_sel_hi:[1,0]
	v_pk_mul_f32 v[86:87], v[86:87], v[150:151]
	global_store_dwordx4 v176, v[84:87], s[8:9] offset:1024
	v_pk_mul_f32 v[88:89], v[88:89], v[164:165] op_sel_hi:[1,0]
	v_pk_mul_f32 v[88:89], v[88:89], v[152:153]
	v_pk_mul_f32 v[90:91], v[90:91], v[164:165] op_sel_hi:[1,0]
	v_pk_mul_f32 v[90:91], v[90:91], v[154:155]
	global_store_dwordx4 v176, v[88:91], s[8:9] offset:2048
	v_pk_mul_f32 v[92:93], v[92:93], v[164:165] op_sel_hi:[1,0]
	v_pk_mul_f32 v[92:93], v[92:93], v[156:157]
	v_pk_mul_f32 v[94:95], v[94:95], v[164:165] op_sel_hi:[1,0]
	v_pk_mul_f32 v[94:95], v[94:95], v[158:159]
	global_store_dwordx4 v176, v[92:95], s[8:9] offset:3072
	s_cmp_le_u32 s3, 3
	s_cbranch_scc1 .Lfin_done
	s_waitcnt vmcnt(24)
	v_mul_f32_e32 v160, v96, v96
	v_mul_f32_e32 v161, v97, v97
	v_mul_f32_e32 v162, v98, v98
	v_mul_f32_e32 v163, v99, v99
	v_fmac_f32_e32 v160, v100, v100
	v_fmac_f32_e32 v161, v101, v101
	v_fmac_f32_e32 v162, v102, v102
	v_fmac_f32_e32 v163, v103, v103
	v_fmac_f32_e32 v160, v104, v104
	v_fmac_f32_e32 v161, v105, v105
	v_fmac_f32_e32 v162, v106, v106
	v_fmac_f32_e32 v163, v107, v107
	v_fmac_f32_e32 v160, v108, v108
	v_fmac_f32_e32 v161, v109, v109
	v_fmac_f32_e32 v162, v110, v110
	v_fmac_f32_e32 v163, v111, v111
	v_fmac_f32_e32 v160, v112, v112
	v_fmac_f32_e32 v161, v113, v113
	v_fmac_f32_e32 v162, v114, v114
	v_fmac_f32_e32 v163, v115, v115
	v_fmac_f32_e32 v160, v116, v116
	v_fmac_f32_e32 v161, v117, v117
	v_fmac_f32_e32 v162, v118, v118
	v_fmac_f32_e32 v163, v119, v119
	v_fmac_f32_e32 v160, v120, v120
	v_fmac_f32_e32 v161, v121, v121
	v_fmac_f32_e32 v162, v122, v122
	v_fmac_f32_e32 v163, v123, v123
	v_fmac_f32_e32 v160, v124, v124
	v_fmac_f32_e32 v161, v125, v125
	v_fmac_f32_e32 v162, v126, v126
	v_fmac_f32_e32 v163, v127, v127
	v_add_f32_e32 v160, v160, v161
	v_add_f32_e32 v162, v162, v163
	v_add_f32_e32 v160, v160, v162
	s_nop 1
	v_add_f32_dpp v160, v160, v160 quad_perm:[1,0,3,2] row_mask:0xf bank_mask:0xf
	s_nop 1
	v_add_f32_dpp v160, v160, v160 quad_perm:[2,3,0,1] row_mask:0xf bank_mask:0xf
	s_nop 1
	v_add_f32_dpp v160, v160, v160 row_half_mirror row_mask:0xf bank_mask:0xf
	s_nop 1
	v_add_f32_dpp v160, v160, v160 row_mirror row_mask:0xf bank_mask:0xf
	s_nop 1
	v_mov_b32_e32 v161, v160
	s_nop 1
	v_permlane16_swap_b32_e32 v160, v161
	s_nop 1
	v_add_f32_e32 v160, v160, v161
	v_mov_b32_e32 v161, v160
	s_nop 1
	v_permlane32_swap_b32_e32 v160, v161
	s_nop 1
	v_add_f32_e32 v164, v160, v161
	v_mov_b32_e32 v170, 0x358637bd
	v_fmamk_f32 v164, v164, 0x3a000000, v170
	v_mul_f32_e32 v165, 0x4f800000, v164
	v_cmp_gt_f32_e32 vcc, 0xf800000, v164
	s_nop 1
	v_cndmask_b32_e32 v164, v164, v165, vcc
	v_sqrt_f32_e32 v165, v164
	s_nop 0
	v_add_u32_e32 v166, -1, v165
	v_fma_f32 v167, -v166, v165, v164
	v_cmp_ge_f32_e64 s[14:15], 0, v167
	v_add_u32_e32 v167, 1, v165
	s_nop 0
	v_cndmask_b32_e64 v166, v165, v166, s[14:15]
	v_fma_f32 v165, -v167, v165, v164
	v_cmp_lt_f32_e64 s[14:15], 0, v165
	s_nop 1
	v_cndmask_b32_e64 v165, v166, v167, s[14:15]
	v_mul_f32_e32 v166, 0x37800000, v165
	v_cndmask_b32_e32 v165, v165, v166, vcc
	v_mov_b32_e32 v171, 0x260
	v_cmp_class_f32_e32 vcc, v164, v171
	s_nop 1
	v_cndmask_b32_e32 v164, v165, v164, vcc
	v_div_scale_f32 v165, s[14:15], v164, v164, 1.0
	v_rcp_f32_e32 v166, v165
	s_nop 1
	v_fma_f32 v167, -v165, v166, 1.0
	v_fmac_f32_e32 v166, v167, v166
	v_div_scale_f32 v167, vcc, 1.0, v164, 1.0
	v_mul_f32_e32 v168, v167, v166
	v_fma_f32 v169, -v165, v168, v167
	v_fmac_f32_e32 v168, v169, v166
	v_fma_f32 v165, -v165, v168, v167
	s_nop 0
	v_div_fmas_f32 v165, v165, v166, v168
	v_div_fixup_f32 v164, v165, v164, 1.0
	s_mul_i32 s6, s12, 3
	s_add_i32 s6, s6, s2
	s_lshl_b32 s6, s6, 13
	v_readlane_b32 s8, v253, 3
	v_readlane_b32 s9, v253, 4
	s_add_u32 s6, s6, 0x1000
	s_add_u32 s8, s8, s6
	s_addc_u32 s9, s9, 0
	v_pk_mul_f32 v[96:97], v[96:97], v[164:165] op_sel_hi:[1,0]
	v_pk_mul_f32 v[96:97], v[96:97], v[128:129]
	v_pk_mul_f32 v[98:99], v[98:99], v[164:165] op_sel_hi:[1,0]
	v_pk_mul_f32 v[98:99], v[98:99], v[130:131]
	global_store_dwordx4 v176, v[96:99], s[8:9] offset:-4096
	v_pk_mul_f32 v[100:101], v[100:101], v[164:165] op_sel_hi:[1,0]
	v_pk_mul_f32 v[100:101], v[100:101], v[132:133]
	v_pk_mul_f32 v[102:103], v[102:103], v[164:165] op_sel_hi:[1,0]
	v_pk_mul_f32 v[102:103], v[102:103], v[134:135]
	global_store_dwordx4 v176, v[100:103], s[8:9] offset:-3072
	v_pk_mul_f32 v[104:105], v[104:105], v[164:165] op_sel_hi:[1,0]
	v_pk_mul_f32 v[104:105], v[104:105], v[136:137]
	v_pk_mul_f32 v[106:107], v[106:107], v[164:165] op_sel_hi:[1,0]
	v_pk_mul_f32 v[106:107], v[106:107], v[138:139]
	global_store_dwordx4 v176, v[104:107], s[8:9] offset:-2048
	v_pk_mul_f32 v[108:109], v[108:109], v[164:165] op_sel_hi:[1,0]
	v_pk_mul_f32 v[108:109], v[108:109], v[140:141]
	v_pk_mul_f32 v[110:111], v[110:111], v[164:165] op_sel_hi:[1,0]
	v_pk_mul_f32 v[110:111], v[110:111], v[142:143]
	global_store_dwordx4 v176, v[108:111], s[8:9] offset:-1024
	v_pk_mul_f32 v[112:113], v[112:113], v[164:165] op_sel_hi:[1,0]
	v_pk_mul_f32 v[112:113], v[112:113], v[144:145]
	v_pk_mul_f32 v[114:115], v[114:115], v[164:165] op_sel_hi:[1,0]
	v_pk_mul_f32 v[114:115], v[114:115], v[146:147]
	global_store_dwordx4 v176, v[112:115], s[8:9] offset:0
	v_pk_mul_f32 v[116:117], v[116:117], v[164:165] op_sel_hi:[1,0]
	v_pk_mul_f32 v[116:117], v[116:117], v[148:149]
	v_pk_mul_f32 v[118:119], v[118:119], v[164:165] op_sel_hi:[1,0]
	v_pk_mul_f32 v[118:119], v[118:119], v[150:151]
	global_store_dwordx4 v176, v[116:119], s[8:9] offset:1024
	v_pk_mul_f32 v[120:121], v[120:121], v[164:165] op_sel_hi:[1,0]
	v_pk_mul_f32 v[120:121], v[120:121], v[152:153]
	v_pk_mul_f32 v[122:123], v[122:123], v[164:165] op_sel_hi:[1,0]
	v_pk_mul_f32 v[122:123], v[122:123], v[154:155]
	global_store_dwordx4 v176, v[120:123], s[8:9] offset:2048
	v_pk_mul_f32 v[124:125], v[124:125], v[164:165] op_sel_hi:[1,0]
	v_pk_mul_f32 v[124:125], v[124:125], v[156:157]
	v_pk_mul_f32 v[126:127], v[126:127], v[164:165] op_sel_hi:[1,0]
	v_pk_mul_f32 v[126:127], v[126:127], v[158:159]
	global_store_dwordx4 v176, v[124:127], s[8:9] offset:3072
.Lfin_done:
.LBB0_1859:
	s_endpgm
